# in-proj q-column epilogue straight-line (no hazard nops, 32-bit store addressing)
# baseline (speedup 1.0000x reference)
.LBB0_592:
	v_mul_lo_u32 v152, v195, s96
	v_lshl_or_b32 v153, s50, 9, v193
	v_add_u32_e32 v152, v152, v153
	v_mul_f32_e32 v164, 0xbfb8aa3b, v128
	v_mul_f32_e32 v165, 0xbfb8aa3b, v129
	v_mul_f32_e32 v166, 0xbfb8aa3b, v130
	v_mul_f32_e32 v167, 0xbfb8aa3b, v131
	v_mul_f32_e32 v168, 0xbfb8aa3b, v124
	v_mul_f32_e32 v169, 0xbfb8aa3b, v125
	v_mul_f32_e32 v170, 0xbfb8aa3b, v126
	v_mul_f32_e32 v171, 0xbfb8aa3b, v127
	v_exp_f32_e32 v164, v164
	v_exp_f32_e32 v165, v165
	v_exp_f32_e32 v166, v166
	v_exp_f32_e32 v167, v167
	v_exp_f32_e32 v168, v168
	v_exp_f32_e32 v169, v169
	v_exp_f32_e32 v170, v170
	v_exp_f32_e32 v171, v171
	v_add_f32_e32 v164, 1.0, v164
	v_add_f32_e32 v165, 1.0, v165
	v_add_f32_e32 v166, 1.0, v166
	v_add_f32_e32 v167, 1.0, v167
	v_add_f32_e32 v168, 1.0, v168
	v_add_f32_e32 v169, 1.0, v169
	v_add_f32_e32 v170, 1.0, v170
	v_add_f32_e32 v171, 1.0, v171
	v_rcp_f32_e32 v164, v164
	v_rcp_f32_e32 v165, v165
	v_rcp_f32_e32 v166, v166
	v_rcp_f32_e32 v167, v167
	v_rcp_f32_e32 v168, v168
	v_rcp_f32_e32 v169, v169
	v_rcp_f32_e32 v170, v170
	v_rcp_f32_e32 v171, v171
	v_mul_f32_e32 v128, v128, v164
	v_mul_f32_e32 v129, v129, v165
	v_mul_f32_e32 v130, v130, v166
	v_mul_f32_e32 v131, v131, v167
	v_mul_f32_e32 v124, v124, v168
	v_mul_f32_e32 v125, v125, v169
	v_mul_f32_e32 v126, v126, v170
	v_mul_f32_e32 v127, v127, v171
	v_cvt_pk_bf16_f32 v128, v128, v129
	v_cvt_pk_bf16_f32 v129, v130, v131
	v_cvt_pk_bf16_f32 v130, v124, v125
	v_cvt_pk_bf16_f32 v131, v126, v127
	global_store_dwordx4 v152, v[128:131], s[42:43] offset:2048
	v_mul_f32_e32 v164, 0xbfb8aa3b, v120
	v_mul_f32_e32 v165, 0xbfb8aa3b, v121
	v_mul_f32_e32 v166, 0xbfb8aa3b, v122
	v_mul_f32_e32 v167, 0xbfb8aa3b, v123
	v_mul_f32_e32 v168, 0xbfb8aa3b, v116
	v_mul_f32_e32 v169, 0xbfb8aa3b, v117
	v_mul_f32_e32 v170, 0xbfb8aa3b, v118
	v_mul_f32_e32 v171, 0xbfb8aa3b, v119
	v_exp_f32_e32 v164, v164
	v_exp_f32_e32 v165, v165
	v_exp_f32_e32 v166, v166
	v_exp_f32_e32 v167, v167
	v_exp_f32_e32 v168, v168
	v_exp_f32_e32 v169, v169
	v_exp_f32_e32 v170, v170
	v_exp_f32_e32 v171, v171
	v_add_f32_e32 v164, 1.0, v164
	v_add_f32_e32 v165, 1.0, v165
	v_add_f32_e32 v166, 1.0, v166
	v_add_f32_e32 v167, 1.0, v167
	v_add_f32_e32 v168, 1.0, v168
	v_add_f32_e32 v169, 1.0, v169
	v_add_f32_e32 v170, 1.0, v170
	v_add_f32_e32 v171, 1.0, v171
	v_rcp_f32_e32 v164, v164
	v_rcp_f32_e32 v165, v165
	v_rcp_f32_e32 v166, v166
	v_rcp_f32_e32 v167, v167
	v_rcp_f32_e32 v168, v168
	v_rcp_f32_e32 v169, v169
	v_rcp_f32_e32 v170, v170
	v_rcp_f32_e32 v171, v171
	v_mul_f32_e32 v120, v120, v164
	v_mul_f32_e32 v121, v121, v165
	v_mul_f32_e32 v122, v122, v166
	v_mul_f32_e32 v123, v123, v167
	v_mul_f32_e32 v116, v116, v168
	v_mul_f32_e32 v117, v117, v169
	v_mul_f32_e32 v118, v118, v170
	v_mul_f32_e32 v119, v119, v171
	v_cvt_pk_bf16_f32 v120, v120, v121
	v_cvt_pk_bf16_f32 v121, v122, v123
	v_cvt_pk_bf16_f32 v122, v116, v117
	v_cvt_pk_bf16_f32 v123, v118, v119
	global_store_dwordx4 v152, v[120:123], s[42:43] offset:2304
	v_add_u32_e32 v152, 0xc000, v152
	v_mul_f32_e32 v164, 0xbfb8aa3b, v112
	v_mul_f32_e32 v165, 0xbfb8aa3b, v113
	v_mul_f32_e32 v166, 0xbfb8aa3b, v114
	v_mul_f32_e32 v167, 0xbfb8aa3b, v115
	v_mul_f32_e32 v168, 0xbfb8aa3b, v108
	v_mul_f32_e32 v169, 0xbfb8aa3b, v109
	v_mul_f32_e32 v170, 0xbfb8aa3b, v110
	v_mul_f32_e32 v171, 0xbfb8aa3b, v111
	v_exp_f32_e32 v164, v164
	v_exp_f32_e32 v165, v165
	v_exp_f32_e32 v166, v166
	v_exp_f32_e32 v167, v167
	v_exp_f32_e32 v168, v168
	v_exp_f32_e32 v169, v169
	v_exp_f32_e32 v170, v170
	v_exp_f32_e32 v171, v171
	v_add_f32_e32 v164, 1.0, v164
	v_add_f32_e32 v165, 1.0, v165
	v_add_f32_e32 v166, 1.0, v166
	v_add_f32_e32 v167, 1.0, v167
	v_add_f32_e32 v168, 1.0, v168
	v_add_f32_e32 v169, 1.0, v169
	v_add_f32_e32 v170, 1.0, v170
	v_add_f32_e32 v171, 1.0, v171
	v_rcp_f32_e32 v164, v164
	v_rcp_f32_e32 v165, v165
	v_rcp_f32_e32 v166, v166
	v_rcp_f32_e32 v167, v167
	v_rcp_f32_e32 v168, v168
	v_rcp_f32_e32 v169, v169
	v_rcp_f32_e32 v170, v170
	v_rcp_f32_e32 v171, v171
	v_mul_f32_e32 v112, v112, v164
	v_mul_f32_e32 v113, v113, v165
	v_mul_f32_e32 v114, v114, v166
	v_mul_f32_e32 v115, v115, v167
	v_mul_f32_e32 v108, v108, v168
	v_mul_f32_e32 v109, v109, v169
	v_mul_f32_e32 v110, v110, v170
	v_mul_f32_e32 v111, v111, v171
	v_cvt_pk_bf16_f32 v112, v112, v113
	v_cvt_pk_bf16_f32 v113, v114, v115
	v_cvt_pk_bf16_f32 v114, v108, v109
	v_cvt_pk_bf16_f32 v115, v110, v111
	global_store_dwordx4 v152, v[112:115], s[42:43] offset:2048
	v_mul_f32_e32 v164, 0xbfb8aa3b, v104
	v_mul_f32_e32 v165, 0xbfb8aa3b, v105
	v_mul_f32_e32 v166, 0xbfb8aa3b, v106
	v_mul_f32_e32 v167, 0xbfb8aa3b, v107
	v_mul_f32_e32 v168, 0xbfb8aa3b, v100
	v_mul_f32_e32 v169, 0xbfb8aa3b, v101
	v_mul_f32_e32 v170, 0xbfb8aa3b, v102
	v_mul_f32_e32 v171, 0xbfb8aa3b, v103
	v_exp_f32_e32 v164, v164
	v_exp_f32_e32 v165, v165
	v_exp_f32_e32 v166, v166
	v_exp_f32_e32 v167, v167
	v_exp_f32_e32 v168, v168
	v_exp_f32_e32 v169, v169
	v_exp_f32_e32 v170, v170
	v_exp_f32_e32 v171, v171
	v_add_f32_e32 v164, 1.0, v164
	v_add_f32_e32 v165, 1.0, v165
	v_add_f32_e32 v166, 1.0, v166
	v_add_f32_e32 v167, 1.0, v167
	v_add_f32_e32 v168, 1.0, v168
	v_add_f32_e32 v169, 1.0, v169
	v_add_f32_e32 v170, 1.0, v170
	v_add_f32_e32 v171, 1.0, v171
	v_rcp_f32_e32 v164, v164
	v_rcp_f32_e32 v165, v165
	v_rcp_f32_e32 v166, v166
	v_rcp_f32_e32 v167, v167
	v_rcp_f32_e32 v168, v168
	v_rcp_f32_e32 v169, v169
	v_rcp_f32_e32 v170, v170
	v_rcp_f32_e32 v171, v171
	v_mul_f32_e32 v104, v104, v164
	v_mul_f32_e32 v105, v105, v165
	v_mul_f32_e32 v106, v106, v166
	v_mul_f32_e32 v107, v107, v167
	v_mul_f32_e32 v100, v100, v168
	v_mul_f32_e32 v101, v101, v169
	v_mul_f32_e32 v102, v102, v170
	v_mul_f32_e32 v103, v103, v171
	v_cvt_pk_bf16_f32 v104, v104, v105
	v_cvt_pk_bf16_f32 v105, v106, v107
	v_cvt_pk_bf16_f32 v106, v100, v101
	v_cvt_pk_bf16_f32 v107, v102, v103
	global_store_dwordx4 v152, v[104:107], s[42:43] offset:2304
	v_add_u32_e32 v152, 0xc000, v152
	v_mul_f32_e32 v164, 0xbfb8aa3b, v96
	v_mul_f32_e32 v165, 0xbfb8aa3b, v97
	v_mul_f32_e32 v166, 0xbfb8aa3b, v98
	v_mul_f32_e32 v167, 0xbfb8aa3b, v99
	v_mul_f32_e32 v168, 0xbfb8aa3b, v92
	v_mul_f32_e32 v169, 0xbfb8aa3b, v93
	v_mul_f32_e32 v170, 0xbfb8aa3b, v94
	v_mul_f32_e32 v171, 0xbfb8aa3b, v95
	v_exp_f32_e32 v164, v164
	v_exp_f32_e32 v165, v165
	v_exp_f32_e32 v166, v166
	v_exp_f32_e32 v167, v167
	v_exp_f32_e32 v168, v168
	v_exp_f32_e32 v169, v169
	v_exp_f32_e32 v170, v170
	v_exp_f32_e32 v171, v171
	v_add_f32_e32 v164, 1.0, v164
	v_add_f32_e32 v165, 1.0, v165
	v_add_f32_e32 v166, 1.0, v166
	v_add_f32_e32 v167, 1.0, v167
	v_add_f32_e32 v168, 1.0, v168
	v_add_f32_e32 v169, 1.0, v169
	v_add_f32_e32 v170, 1.0, v170
	v_add_f32_e32 v171, 1.0, v171
	v_rcp_f32_e32 v164, v164
	v_rcp_f32_e32 v165, v165
	v_rcp_f32_e32 v166, v166
	v_rcp_f32_e32 v167, v167
	v_rcp_f32_e32 v168, v168
	v_rcp_f32_e32 v169, v169
	v_rcp_f32_e32 v170, v170
	v_rcp_f32_e32 v171, v171
	v_mul_f32_e32 v96, v96, v164
	v_mul_f32_e32 v97, v97, v165
	v_mul_f32_e32 v98, v98, v166
	v_mul_f32_e32 v99, v99, v167
	v_mul_f32_e32 v92, v92, v168
	v_mul_f32_e32 v93, v93, v169
	v_mul_f32_e32 v94, v94, v170
	v_mul_f32_e32 v95, v95, v171
	v_cvt_pk_bf16_f32 v96, v96, v97
	v_cvt_pk_bf16_f32 v97, v98, v99
	v_cvt_pk_bf16_f32 v98, v92, v93
	v_cvt_pk_bf16_f32 v99, v94, v95
	global_store_dwordx4 v152, v[96:99], s[42:43] offset:2048
	v_mul_f32_e32 v164, 0xbfb8aa3b, v88
	v_mul_f32_e32 v165, 0xbfb8aa3b, v89
	v_mul_f32_e32 v166, 0xbfb8aa3b, v90
	v_mul_f32_e32 v167, 0xbfb8aa3b, v91
	v_mul_f32_e32 v168, 0xbfb8aa3b, v84
	v_mul_f32_e32 v169, 0xbfb8aa3b, v85
	v_mul_f32_e32 v170, 0xbfb8aa3b, v86
	v_mul_f32_e32 v171, 0xbfb8aa3b, v87
	v_exp_f32_e32 v164, v164
	v_exp_f32_e32 v165, v165
	v_exp_f32_e32 v166, v166
	v_exp_f32_e32 v167, v167
	v_exp_f32_e32 v168, v168
	v_exp_f32_e32 v169, v169
	v_exp_f32_e32 v170, v170
	v_exp_f32_e32 v171, v171
	v_add_f32_e32 v164, 1.0, v164
	v_add_f32_e32 v165, 1.0, v165
	v_add_f32_e32 v166, 1.0, v166
	v_add_f32_e32 v167, 1.0, v167
	v_add_f32_e32 v168, 1.0, v168
	v_add_f32_e32 v169, 1.0, v169
	v_add_f32_e32 v170, 1.0, v170
	v_add_f32_e32 v171, 1.0, v171
	v_rcp_f32_e32 v164, v164
	v_rcp_f32_e32 v165, v165
	v_rcp_f32_e32 v166, v166
	v_rcp_f32_e32 v167, v167
	v_rcp_f32_e32 v168, v168
	v_rcp_f32_e32 v169, v169
	v_rcp_f32_e32 v170, v170
	v_rcp_f32_e32 v171, v171
	v_mul_f32_e32 v88, v88, v164
	v_mul_f32_e32 v89, v89, v165
	v_mul_f32_e32 v90, v90, v166
	v_mul_f32_e32 v91, v91, v167
	v_mul_f32_e32 v84, v84, v168
	v_mul_f32_e32 v85, v85, v169
	v_mul_f32_e32 v86, v86, v170
	v_mul_f32_e32 v87, v87, v171
	v_cvt_pk_bf16_f32 v88, v88, v89
	v_cvt_pk_bf16_f32 v89, v90, v91
	v_cvt_pk_bf16_f32 v90, v84, v85
	v_cvt_pk_bf16_f32 v91, v86, v87
	global_store_dwordx4 v152, v[88:91], s[42:43] offset:2304
	v_add_u32_e32 v152, 0xc000, v152
	v_mul_f32_e32 v164, 0xbfb8aa3b, v80
	v_mul_f32_e32 v165, 0xbfb8aa3b, v81
	v_mul_f32_e32 v166, 0xbfb8aa3b, v82
	v_mul_f32_e32 v167, 0xbfb8aa3b, v83
	v_mul_f32_e32 v168, 0xbfb8aa3b, v76
	v_mul_f32_e32 v169, 0xbfb8aa3b, v77
	v_mul_f32_e32 v170, 0xbfb8aa3b, v78
	v_mul_f32_e32 v171, 0xbfb8aa3b, v79
	v_exp_f32_e32 v164, v164
	v_exp_f32_e32 v165, v165
	v_exp_f32_e32 v166, v166
	v_exp_f32_e32 v167, v167
	v_exp_f32_e32 v168, v168
	v_exp_f32_e32 v169, v169
	v_exp_f32_e32 v170, v170
	v_exp_f32_e32 v171, v171
	v_add_f32_e32 v164, 1.0, v164
	v_add_f32_e32 v165, 1.0, v165
	v_add_f32_e32 v166, 1.0, v166
	v_add_f32_e32 v167, 1.0, v167
	v_add_f32_e32 v168, 1.0, v168
	v_add_f32_e32 v169, 1.0, v169
	v_add_f32_e32 v170, 1.0, v170
	v_add_f32_e32 v171, 1.0, v171
	v_rcp_f32_e32 v164, v164
	v_rcp_f32_e32 v165, v165
	v_rcp_f32_e32 v166, v166
	v_rcp_f32_e32 v167, v167
	v_rcp_f32_e32 v168, v168
	v_rcp_f32_e32 v169, v169
	v_rcp_f32_e32 v170, v170
	v_rcp_f32_e32 v171, v171
	v_mul_f32_e32 v80, v80, v164
	v_mul_f32_e32 v81, v81, v165
	v_mul_f32_e32 v82, v82, v166
	v_mul_f32_e32 v83, v83, v167
	v_mul_f32_e32 v76, v76, v168
	v_mul_f32_e32 v77, v77, v169
	v_mul_f32_e32 v78, v78, v170
	v_mul_f32_e32 v79, v79, v171
	v_cvt_pk_bf16_f32 v80, v80, v81
	v_cvt_pk_bf16_f32 v81, v82, v83
	v_cvt_pk_bf16_f32 v82, v76, v77
	v_cvt_pk_bf16_f32 v83, v78, v79
	global_store_dwordx4 v152, v[80:83], s[42:43] offset:2048
	v_mul_f32_e32 v164, 0xbfb8aa3b, v72
	v_mul_f32_e32 v165, 0xbfb8aa3b, v73
	v_mul_f32_e32 v166, 0xbfb8aa3b, v74
	v_mul_f32_e32 v167, 0xbfb8aa3b, v75
	v_mul_f32_e32 v168, 0xbfb8aa3b, v68
	v_mul_f32_e32 v169, 0xbfb8aa3b, v69
	v_mul_f32_e32 v170, 0xbfb8aa3b, v70
	v_mul_f32_e32 v171, 0xbfb8aa3b, v71
	v_exp_f32_e32 v164, v164
	v_exp_f32_e32 v165, v165
	v_exp_f32_e32 v166, v166
	v_exp_f32_e32 v167, v167
	v_exp_f32_e32 v168, v168
	v_exp_f32_e32 v169, v169
	v_exp_f32_e32 v170, v170
	v_exp_f32_e32 v171, v171
	v_add_f32_e32 v164, 1.0, v164
	v_add_f32_e32 v165, 1.0, v165
	v_add_f32_e32 v166, 1.0, v166
	v_add_f32_e32 v167, 1.0, v167
	v_add_f32_e32 v168, 1.0, v168
	v_add_f32_e32 v169, 1.0, v169
	v_add_f32_e32 v170, 1.0, v170
	v_add_f32_e32 v171, 1.0, v171
	v_rcp_f32_e32 v164, v164
	v_rcp_f32_e32 v165, v165
	v_rcp_f32_e32 v166, v166
	v_rcp_f32_e32 v167, v167
	v_rcp_f32_e32 v168, v168
	v_rcp_f32_e32 v169, v169
	v_rcp_f32_e32 v170, v170
	v_rcp_f32_e32 v171, v171
	v_mul_f32_e32 v72, v72, v164
	v_mul_f32_e32 v73, v73, v165
	v_mul_f32_e32 v74, v74, v166
	v_mul_f32_e32 v75, v75, v167
	v_mul_f32_e32 v68, v68, v168
	v_mul_f32_e32 v69, v69, v169
	v_mul_f32_e32 v70, v70, v170
	v_mul_f32_e32 v71, v71, v171
	v_cvt_pk_bf16_f32 v72, v72, v73
	v_cvt_pk_bf16_f32 v73, v74, v75
	v_cvt_pk_bf16_f32 v74, v68, v69
	v_cvt_pk_bf16_f32 v75, v70, v71
	global_store_dwordx4 v152, v[72:75], s[42:43] offset:2304
	v_add_u32_e32 v152, 0x3c000, v152
	v_mul_f32_e32 v164, 0xbfb8aa3b, v64
	v_mul_f32_e32 v165, 0xbfb8aa3b, v65
	v_mul_f32_e32 v166, 0xbfb8aa3b, v66
	v_mul_f32_e32 v167, 0xbfb8aa3b, v67
	v_mul_f32_e32 v168, 0xbfb8aa3b, v60
	v_mul_f32_e32 v169, 0xbfb8aa3b, v61
	v_mul_f32_e32 v170, 0xbfb8aa3b, v62
	v_mul_f32_e32 v171, 0xbfb8aa3b, v63
	v_exp_f32_e32 v164, v164
	v_exp_f32_e32 v165, v165
	v_exp_f32_e32 v166, v166
	v_exp_f32_e32 v167, v167
	v_exp_f32_e32 v168, v168
	v_exp_f32_e32 v169, v169
	v_exp_f32_e32 v170, v170
	v_exp_f32_e32 v171, v171
	v_add_f32_e32 v164, 1.0, v164
	v_add_f32_e32 v165, 1.0, v165
	v_add_f32_e32 v166, 1.0, v166
	v_add_f32_e32 v167, 1.0, v167
	v_add_f32_e32 v168, 1.0, v168
	v_add_f32_e32 v169, 1.0, v169
	v_add_f32_e32 v170, 1.0, v170
	v_add_f32_e32 v171, 1.0, v171
	v_rcp_f32_e32 v164, v164
	v_rcp_f32_e32 v165, v165
	v_rcp_f32_e32 v166, v166
	v_rcp_f32_e32 v167, v167
	v_rcp_f32_e32 v168, v168
	v_rcp_f32_e32 v169, v169
	v_rcp_f32_e32 v170, v170
	v_rcp_f32_e32 v171, v171
	v_mul_f32_e32 v64, v64, v164
	v_mul_f32_e32 v65, v65, v165
	v_mul_f32_e32 v66, v66, v166
	v_mul_f32_e32 v67, v67, v167
	v_mul_f32_e32 v60, v60, v168
	v_mul_f32_e32 v61, v61, v169
	v_mul_f32_e32 v62, v62, v170
	v_mul_f32_e32 v63, v63, v171
	v_cvt_pk_bf16_f32 v64, v64, v65
	v_cvt_pk_bf16_f32 v65, v66, v67
	v_cvt_pk_bf16_f32 v66, v60, v61
	v_cvt_pk_bf16_f32 v67, v62, v63
	global_store_dwordx4 v152, v[64:67], s[42:43] offset:2048
	v_mul_f32_e32 v164, 0xbfb8aa3b, v56
	v_mul_f32_e32 v165, 0xbfb8aa3b, v57
	v_mul_f32_e32 v166, 0xbfb8aa3b, v58
	v_mul_f32_e32 v167, 0xbfb8aa3b, v59
	v_mul_f32_e32 v168, 0xbfb8aa3b, v52
	v_mul_f32_e32 v169, 0xbfb8aa3b, v53
	v_mul_f32_e32 v170, 0xbfb8aa3b, v54
	v_mul_f32_e32 v171, 0xbfb8aa3b, v55
	v_exp_f32_e32 v164, v164
	v_exp_f32_e32 v165, v165
	v_exp_f32_e32 v166, v166
	v_exp_f32_e32 v167, v167
	v_exp_f32_e32 v168, v168
	v_exp_f32_e32 v169, v169
	v_exp_f32_e32 v170, v170
	v_exp_f32_e32 v171, v171
	v_add_f32_e32 v164, 1.0, v164
	v_add_f32_e32 v165, 1.0, v165
	v_add_f32_e32 v166, 1.0, v166
	v_add_f32_e32 v167, 1.0, v167
	v_add_f32_e32 v168, 1.0, v168
	v_add_f32_e32 v169, 1.0, v169
	v_add_f32_e32 v170, 1.0, v170
	v_add_f32_e32 v171, 1.0, v171
	v_rcp_f32_e32 v164, v164
	v_rcp_f32_e32 v165, v165
	v_rcp_f32_e32 v166, v166
	v_rcp_f32_e32 v167, v167
	v_rcp_f32_e32 v168, v168
	v_rcp_f32_e32 v169, v169
	v_rcp_f32_e32 v170, v170
	v_rcp_f32_e32 v171, v171
	v_mul_f32_e32 v56, v56, v164
	v_mul_f32_e32 v57, v57, v165
	v_mul_f32_e32 v58, v58, v166
	v_mul_f32_e32 v59, v59, v167
	v_mul_f32_e32 v52, v52, v168
	v_mul_f32_e32 v53, v53, v169
	v_mul_f32_e32 v54, v54, v170
	v_mul_f32_e32 v55, v55, v171
	v_cvt_pk_bf16_f32 v56, v56, v57
	v_cvt_pk_bf16_f32 v57, v58, v59
	v_cvt_pk_bf16_f32 v58, v52, v53
	v_cvt_pk_bf16_f32 v59, v54, v55
	global_store_dwordx4 v152, v[56:59], s[42:43] offset:2304
	v_add_u32_e32 v152, 0xc000, v152
	v_mul_f32_e32 v164, 0xbfb8aa3b, v48
	v_mul_f32_e32 v165, 0xbfb8aa3b, v49
	v_mul_f32_e32 v166, 0xbfb8aa3b, v50
	v_mul_f32_e32 v167, 0xbfb8aa3b, v51
	v_mul_f32_e32 v168, 0xbfb8aa3b, v44
	v_mul_f32_e32 v169, 0xbfb8aa3b, v45
	v_mul_f32_e32 v170, 0xbfb8aa3b, v46
	v_mul_f32_e32 v171, 0xbfb8aa3b, v47
	v_exp_f32_e32 v164, v164
	v_exp_f32_e32 v165, v165
	v_exp_f32_e32 v166, v166
	v_exp_f32_e32 v167, v167
	v_exp_f32_e32 v168, v168
	v_exp_f32_e32 v169, v169
	v_exp_f32_e32 v170, v170
	v_exp_f32_e32 v171, v171
	v_add_f32_e32 v164, 1.0, v164
	v_add_f32_e32 v165, 1.0, v165
	v_add_f32_e32 v166, 1.0, v166
	v_add_f32_e32 v167, 1.0, v167
	v_add_f32_e32 v168, 1.0, v168
	v_add_f32_e32 v169, 1.0, v169
	v_add_f32_e32 v170, 1.0, v170
	v_add_f32_e32 v171, 1.0, v171
	v_rcp_f32_e32 v164, v164
	v_rcp_f32_e32 v165, v165
	v_rcp_f32_e32 v166, v166
	v_rcp_f32_e32 v167, v167
	v_rcp_f32_e32 v168, v168
	v_rcp_f32_e32 v169, v169
	v_rcp_f32_e32 v170, v170
	v_rcp_f32_e32 v171, v171
	v_mul_f32_e32 v48, v48, v164
	v_mul_f32_e32 v49, v49, v165
	v_mul_f32_e32 v50, v50, v166
	v_mul_f32_e32 v51, v51, v167
	v_mul_f32_e32 v44, v44, v168
	v_mul_f32_e32 v45, v45, v169
	v_mul_f32_e32 v46, v46, v170
	v_mul_f32_e32 v47, v47, v171
	v_cvt_pk_bf16_f32 v48, v48, v49
	v_cvt_pk_bf16_f32 v49, v50, v51
	v_cvt_pk_bf16_f32 v50, v44, v45
	v_cvt_pk_bf16_f32 v51, v46, v47
	global_store_dwordx4 v152, v[48:51], s[42:43] offset:2048
	v_mul_f32_e32 v164, 0xbfb8aa3b, v40
	v_mul_f32_e32 v165, 0xbfb8aa3b, v41
	v_mul_f32_e32 v166, 0xbfb8aa3b, v42
	v_mul_f32_e32 v167, 0xbfb8aa3b, v43
	v_mul_f32_e32 v168, 0xbfb8aa3b, v36
	v_mul_f32_e32 v169, 0xbfb8aa3b, v37
	v_mul_f32_e32 v170, 0xbfb8aa3b, v38
	v_mul_f32_e32 v171, 0xbfb8aa3b, v39
	v_exp_f32_e32 v164, v164
	v_exp_f32_e32 v165, v165
	v_exp_f32_e32 v166, v166
	v_exp_f32_e32 v167, v167
	v_exp_f32_e32 v168, v168
	v_exp_f32_e32 v169, v169
	v_exp_f32_e32 v170, v170
	v_exp_f32_e32 v171, v171
	v_add_f32_e32 v164, 1.0, v164
	v_add_f32_e32 v165, 1.0, v165
	v_add_f32_e32 v166, 1.0, v166
	v_add_f32_e32 v167, 1.0, v167
	v_add_f32_e32 v168, 1.0, v168
	v_add_f32_e32 v169, 1.0, v169
	v_add_f32_e32 v170, 1.0, v170
	v_add_f32_e32 v171, 1.0, v171
	v_rcp_f32_e32 v164, v164
	v_rcp_f32_e32 v165, v165
	v_rcp_f32_e32 v166, v166
	v_rcp_f32_e32 v167, v167
	v_rcp_f32_e32 v168, v168
	v_rcp_f32_e32 v169, v169
	v_rcp_f32_e32 v170, v170
	v_rcp_f32_e32 v171, v171
	v_mul_f32_e32 v40, v40, v164
	v_mul_f32_e32 v41, v41, v165
	v_mul_f32_e32 v42, v42, v166
	v_mul_f32_e32 v43, v43, v167
	v_mul_f32_e32 v36, v36, v168
	v_mul_f32_e32 v37, v37, v169
	v_mul_f32_e32 v38, v38, v170
	v_mul_f32_e32 v39, v39, v171
	v_cvt_pk_bf16_f32 v40, v40, v41
	v_cvt_pk_bf16_f32 v41, v42, v43
	v_cvt_pk_bf16_f32 v42, v36, v37
	v_cvt_pk_bf16_f32 v43, v38, v39
	global_store_dwordx4 v152, v[40:43], s[42:43] offset:2304
	v_add_u32_e32 v152, 0xc000, v152
	v_mul_f32_e32 v164, 0xbfb8aa3b, v32
	v_mul_f32_e32 v165, 0xbfb8aa3b, v33
	v_mul_f32_e32 v166, 0xbfb8aa3b, v34
	v_mul_f32_e32 v167, 0xbfb8aa3b, v35
	v_mul_f32_e32 v168, 0xbfb8aa3b, v28
	v_mul_f32_e32 v169, 0xbfb8aa3b, v29
	v_mul_f32_e32 v170, 0xbfb8aa3b, v30
	v_mul_f32_e32 v171, 0xbfb8aa3b, v31
	v_exp_f32_e32 v164, v164
	v_exp_f32_e32 v165, v165
	v_exp_f32_e32 v166, v166
	v_exp_f32_e32 v167, v167
	v_exp_f32_e32 v168, v168
	v_exp_f32_e32 v169, v169
	v_exp_f32_e32 v170, v170
	v_exp_f32_e32 v171, v171
	v_add_f32_e32 v164, 1.0, v164
	v_add_f32_e32 v165, 1.0, v165
	v_add_f32_e32 v166, 1.0, v166
	v_add_f32_e32 v167, 1.0, v167
	v_add_f32_e32 v168, 1.0, v168
	v_add_f32_e32 v169, 1.0, v169
	v_add_f32_e32 v170, 1.0, v170
	v_add_f32_e32 v171, 1.0, v171
	v_rcp_f32_e32 v164, v164
	v_rcp_f32_e32 v165, v165
	v_rcp_f32_e32 v166, v166
	v_rcp_f32_e32 v167, v167
	v_rcp_f32_e32 v168, v168
	v_rcp_f32_e32 v169, v169
	v_rcp_f32_e32 v170, v170
	v_rcp_f32_e32 v171, v171
	v_mul_f32_e32 v32, v32, v164
	v_mul_f32_e32 v33, v33, v165
	v_mul_f32_e32 v34, v34, v166
	v_mul_f32_e32 v35, v35, v167
	v_mul_f32_e32 v28, v28, v168
	v_mul_f32_e32 v29, v29, v169
	v_mul_f32_e32 v30, v30, v170
	v_mul_f32_e32 v31, v31, v171
	v_cvt_pk_bf16_f32 v32, v32, v33
	v_cvt_pk_bf16_f32 v33, v34, v35
	v_cvt_pk_bf16_f32 v34, v28, v29
	v_cvt_pk_bf16_f32 v35, v30, v31
	global_store_dwordx4 v152, v[32:35], s[42:43] offset:2048
	v_mul_f32_e32 v164, 0xbfb8aa3b, v24
	v_mul_f32_e32 v165, 0xbfb8aa3b, v25
	v_mul_f32_e32 v166, 0xbfb8aa3b, v26
	v_mul_f32_e32 v167, 0xbfb8aa3b, v27
	v_mul_f32_e32 v168, 0xbfb8aa3b, v20
	v_mul_f32_e32 v169, 0xbfb8aa3b, v21
	v_mul_f32_e32 v170, 0xbfb8aa3b, v22
	v_mul_f32_e32 v171, 0xbfb8aa3b, v23
	v_exp_f32_e32 v164, v164
	v_exp_f32_e32 v165, v165
	v_exp_f32_e32 v166, v166
	v_exp_f32_e32 v167, v167
	v_exp_f32_e32 v168, v168
	v_exp_f32_e32 v169, v169
	v_exp_f32_e32 v170, v170
	v_exp_f32_e32 v171, v171
	v_add_f32_e32 v164, 1.0, v164
	v_add_f32_e32 v165, 1.0, v165
	v_add_f32_e32 v166, 1.0, v166
	v_add_f32_e32 v167, 1.0, v167
	v_add_f32_e32 v168, 1.0, v168
	v_add_f32_e32 v169, 1.0, v169
	v_add_f32_e32 v170, 1.0, v170
	v_add_f32_e32 v171, 1.0, v171
	v_rcp_f32_e32 v164, v164
	v_rcp_f32_e32 v165, v165
	v_rcp_f32_e32 v166, v166
	v_rcp_f32_e32 v167, v167
	v_rcp_f32_e32 v168, v168
	v_rcp_f32_e32 v169, v169
	v_rcp_f32_e32 v170, v170
	v_rcp_f32_e32 v171, v171
	v_mul_f32_e32 v24, v24, v164
	v_mul_f32_e32 v25, v25, v165
	v_mul_f32_e32 v26, v26, v166
	v_mul_f32_e32 v27, v27, v167
	v_mul_f32_e32 v20, v20, v168
	v_mul_f32_e32 v21, v21, v169
	v_mul_f32_e32 v22, v22, v170
	v_mul_f32_e32 v23, v23, v171
	v_cvt_pk_bf16_f32 v24, v24, v25
	v_cvt_pk_bf16_f32 v25, v26, v27
	v_cvt_pk_bf16_f32 v26, v20, v21
	v_cvt_pk_bf16_f32 v27, v22, v23
	global_store_dwordx4 v152, v[24:27], s[42:43] offset:2304
	v_add_u32_e32 v152, 0xc000, v152
	v_mul_f32_e32 v164, 0xbfb8aa3b, v16
	v_mul_f32_e32 v165, 0xbfb8aa3b, v17
	v_mul_f32_e32 v166, 0xbfb8aa3b, v18
	v_mul_f32_e32 v167, 0xbfb8aa3b, v19
	v_mul_f32_e32 v168, 0xbfb8aa3b, v12
	v_mul_f32_e32 v169, 0xbfb8aa3b, v13
	v_mul_f32_e32 v170, 0xbfb8aa3b, v14
	v_mul_f32_e32 v171, 0xbfb8aa3b, v15
	v_exp_f32_e32 v164, v164
	v_exp_f32_e32 v165, v165
	v_exp_f32_e32 v166, v166
	v_exp_f32_e32 v167, v167
	v_exp_f32_e32 v168, v168
	v_exp_f32_e32 v169, v169
	v_exp_f32_e32 v170, v170
	v_exp_f32_e32 v171, v171
	v_add_f32_e32 v164, 1.0, v164
	v_add_f32_e32 v165, 1.0, v165
	v_add_f32_e32 v166, 1.0, v166
	v_add_f32_e32 v167, 1.0, v167
	v_add_f32_e32 v168, 1.0, v168
	v_add_f32_e32 v169, 1.0, v169
	v_add_f32_e32 v170, 1.0, v170
	v_add_f32_e32 v171, 1.0, v171
	v_rcp_f32_e32 v164, v164
	v_rcp_f32_e32 v165, v165
	v_rcp_f32_e32 v166, v166
	v_rcp_f32_e32 v167, v167
	v_rcp_f32_e32 v168, v168
	v_rcp_f32_e32 v169, v169
	v_rcp_f32_e32 v170, v170
	v_rcp_f32_e32 v171, v171
	v_mul_f32_e32 v16, v16, v164
	v_mul_f32_e32 v17, v17, v165
	v_mul_f32_e32 v18, v18, v166
	v_mul_f32_e32 v19, v19, v167
	v_mul_f32_e32 v12, v12, v168
	v_mul_f32_e32 v13, v13, v169
	v_mul_f32_e32 v14, v14, v170
	v_mul_f32_e32 v15, v15, v171
	v_cvt_pk_bf16_f32 v16, v16, v17
	v_cvt_pk_bf16_f32 v17, v18, v19
	v_cvt_pk_bf16_f32 v18, v12, v13
	v_cvt_pk_bf16_f32 v19, v14, v15
	global_store_dwordx4 v152, v[16:19], s[42:43] offset:2048
	v_mul_f32_e32 v164, 0xbfb8aa3b, v8
	v_mul_f32_e32 v165, 0xbfb8aa3b, v9
	v_mul_f32_e32 v166, 0xbfb8aa3b, v10
	v_mul_f32_e32 v167, 0xbfb8aa3b, v11
	v_mul_f32_e32 v168, 0xbfb8aa3b, v4
	v_mul_f32_e32 v169, 0xbfb8aa3b, v5
	v_mul_f32_e32 v170, 0xbfb8aa3b, v6
	v_mul_f32_e32 v171, 0xbfb8aa3b, v7
	v_exp_f32_e32 v164, v164
	v_exp_f32_e32 v165, v165
	v_exp_f32_e32 v166, v166
	v_exp_f32_e32 v167, v167
	v_exp_f32_e32 v168, v168
	v_exp_f32_e32 v169, v169
	v_exp_f32_e32 v170, v170
	v_exp_f32_e32 v171, v171
	v_add_f32_e32 v164, 1.0, v164
	v_add_f32_e32 v165, 1.0, v165
	v_add_f32_e32 v166, 1.0, v166
	v_add_f32_e32 v167, 1.0, v167
	v_add_f32_e32 v168, 1.0, v168
	v_add_f32_e32 v169, 1.0, v169
	v_add_f32_e32 v170, 1.0, v170
	v_add_f32_e32 v171, 1.0, v171
	v_rcp_f32_e32 v164, v164
	v_rcp_f32_e32 v165, v165
	v_rcp_f32_e32 v166, v166
	v_rcp_f32_e32 v167, v167
	v_rcp_f32_e32 v168, v168
	v_rcp_f32_e32 v169, v169
	v_rcp_f32_e32 v170, v170
	v_rcp_f32_e32 v171, v171
	v_mul_f32_e32 v8, v8, v164
	v_mul_f32_e32 v9, v9, v165
	v_mul_f32_e32 v10, v10, v166
	v_mul_f32_e32 v11, v11, v167
	v_mul_f32_e32 v4, v4, v168
	v_mul_f32_e32 v5, v5, v169
	v_mul_f32_e32 v6, v6, v170
	v_mul_f32_e32 v7, v7, v171
	v_cvt_pk_bf16_f32 v8, v8, v9
	v_cvt_pk_bf16_f32 v9, v10, v11
	v_cvt_pk_bf16_f32 v10, v4, v5
	v_cvt_pk_bf16_f32 v11, v6, v7
	global_store_dwordx4 v152, v[8:11], s[42:43] offset:2304
	s_andn2_b64 vcc, exec, s[38:39]
	s_mov_b64 s[2:3], -1
	s_cbranch_vccnz .LBB0_430
